# glapost: token loop software-pipelined (next token's 6 loads issued before current token's arithmetic, via spare VGPRs)
# baseline (speedup 1.0000x reference)
.LBB0_489:
	s_cmp_gt_i32 s44, 5
	s_cselect_b64 s[2:3], -1, 0
	s_cmp_lt_i32 s45, 6
	s_cselect_b64 s[4:5], -1, 0
	s_or_b64 s[2:3], s[2:3], s[4:5]
	v_bfe_u32 v131, v0, 6, 4
	s_and_b64 vcc, exec, s[2:3]
	v_lshl_or_b32 v130, s66, 2, v131
	s_cbranch_vccnz .LBB0_547
	s_load_dword s33, s[0:1], 0xf0
	s_waitcnt vmcnt(1)
	v_lshl_or_b32 v26, s66, 2, v131
	s_add_u32 s2, s0, 0xf0
	s_movk_i32 s4, 0x3000
	v_and_b32_e32 v1, 0x3ff, v0
	s_addc_u32 s3, s1, 0
	v_cmp_gt_i32_e32 vcc, s4, v26
	s_and_saveexec_b64 s[46:47], vcc
	s_cbranch_execz .LBB0_493
	v_mbcnt_lo_u32_b32 v2, -1, 0
	v_mbcnt_hi_u32_b32 v2, -1, v2
	v_and_b32_e32 v4, 64, v2
	v_xor_b32_e32 v3, 1, v2
	v_add_u32_e32 v4, 64, v4
	v_cmp_lt_i32_e32 vcc, v3, v4
	v_ashrrev_i32_e32 v27, 31, v26
	s_waitcnt lgkmcnt(0)
	s_lshl_b32 s48, s33, 2
	v_cndmask_b32_e32 v3, v2, v3, vcc
	v_lshlrev_b32_e32 v42, 2, v3
	v_xor_b32_e32 v3, 2, v2
	v_cmp_lt_i32_e32 vcc, v3, v4
	s_mov_b64 s[4:5], 0x18d2401c
	s_ashr_i32 s49, s48, 31
	v_cndmask_b32_e32 v3, v2, v3, vcc
	v_lshlrev_b32_e32 v43, 2, v3
	v_xor_b32_e32 v3, 4, v2
	v_cmp_lt_i32_e32 vcc, v3, v4
	s_mov_b32 s54, 0xfe7fffe4
	s_mov_b32 s56, 0xf85fffe4
	v_cndmask_b32_e32 v3, v2, v3, vcc
	v_lshlrev_b32_e32 v44, 2, v3
	v_xor_b32_e32 v3, 8, v2
	v_cmp_lt_i32_e32 vcc, v3, v4
	v_and_b32_e32 v4, 63, v1
	s_lshl_b64 s[50:51], s[48:49], 11
	v_cndmask_b32_e32 v2, v2, v3, vcc
	v_lshlrev_b32_e32 v45, 2, v2
	v_lshlrev_b32_e32 v2, 6, v1
	v_and_b32_e32 v2, 0x3c0, v2
	v_mov_b32_e32 v3, 0
	v_lshl_add_u64 v[28:29], s[92:93], 0, v[2:3]
	v_lshlrev_b64 v[2:3], 11, v[26:27]
	v_lshl_or_b32 v2, v4, 5, v2
	v_lshl_add_u64 v[2:3], s[42:43], 0, v[2:3]
	s_waitcnt vmcnt(0)
	v_lshl_add_u64 v[30:31], v[2:3], 0, s[4:5]
	s_mov_b64 s[52:53], 0
	s_mov_b32 s55, -1
	s_mov_b32 s57, -1
	s_mov_b32 s49, 0xf8600000
	v_mov_b32_e32 v27, 0x358637bd
	s_mov_b32 s58, 0x800000
	s_movk_i32 s59, 0x2fff
	s_mov_b32 s98, 0xfe800000
	s_mov_b32 s99, -1
	s_mov_b32 s100, 0xf8600000
	s_mov_b32 s101, -1
	global_load_dwordx4 v[200:203], v[30:31], off offset:-12
	global_load_dwordx4 v[204:207], v[30:31], off offset:-28
	v_lshl_add_u64 v[208:209], v[30:31], 0, s[98:99]
	global_load_dwordx4 v[208:211], v[208:209], off offset:-28
	v_lshl_add_u64 v[212:213], v[30:31], 0, s[54:55]
	global_load_dwordx4 v[212:215], v[212:213], off offset:16
	v_lshl_add_u64 v[216:217], v[30:31], 0, s[100:101]
	global_load_dwordx4 v[216:219], v[216:217], off offset:-28
	v_lshl_add_u64 v[220:221], v[30:31], 0, s[56:57]
	global_load_dwordx4 v[220:223], v[220:221], off offset:16
	s_waitcnt vmcnt(0)
.LBB0_492:
	v_lshl_add_u64 v[32:33], v[30:31], 0, s[98:99]
	v_mov_b32_e32 v18, v200
	v_mov_b32_e32 v19, v201
	v_mov_b32_e32 v20, v202
	v_mov_b32_e32 v21, v203
	v_mov_b32_e32 v22, v204
	v_mov_b32_e32 v23, v205
	v_mov_b32_e32 v24, v206
	v_mov_b32_e32 v25, v207
	v_mov_b32_e32 v38, v208
	v_mov_b32_e32 v39, v209
	v_mov_b32_e32 v40, v210
	v_mov_b32_e32 v41, v211
	v_mov_b32_e32 v46, v212
	v_mov_b32_e32 v47, v213
	v_mov_b32_e32 v48, v214
	v_mov_b32_e32 v49, v215
	v_mov_b32_e32 v50, v216
	v_mov_b32_e32 v51, v217
	v_mov_b32_e32 v52, v218
	v_mov_b32_e32 v53, v219
	v_mov_b32_e32 v34, v220
	v_mov_b32_e32 v35, v221
	v_mov_b32_e32 v36, v222
	v_mov_b32_e32 v37, v223
	global_load_dwordx4 v[2:5], v[28:29], off offset:48
	global_load_dwordx4 v[6:9], v[28:29], off offset:32
	global_load_dwordx4 v[10:13], v[28:29], off offset:16
	global_load_dwordx4 v[14:17], v[28:29], off
	v_add_u32_e32 v26, s48, v26
	v_cmp_lt_i32_e64 s[4:5], s59, v26
	s_or_b64 s[52:53], s[4:5], s[52:53]
	v_lshl_add_u64 v[30:31], v[30:31], 0, s[50:51]
	global_load_dwordx4 v[200:203], v[30:31], off offset:-12
	global_load_dwordx4 v[204:207], v[30:31], off offset:-28
	v_lshl_add_u64 v[208:209], v[30:31], 0, s[98:99]
	global_load_dwordx4 v[208:211], v[208:209], off offset:-28
	v_lshl_add_u64 v[212:213], v[30:31], 0, s[54:55]
	global_load_dwordx4 v[212:215], v[212:213], off offset:16
	v_lshl_add_u64 v[216:217], v[30:31], 0, s[100:101]
	global_load_dwordx4 v[216:219], v[216:217], off offset:-28
	v_lshl_add_u64 v[220:221], v[30:31], 0, s[56:57]
	global_load_dwordx4 v[220:223], v[220:221], off offset:16
	s_waitcnt vmcnt(6)
	v_lshlrev_b32_e32 v62, 16, v20
	v_lshlrev_b32_e32 v54, 16, v22
	v_and_b32_e32 v55, 0xffff0000, v22
	v_lshlrev_b32_e32 v56, 16, v23
	v_and_b32_e32 v57, 0xffff0000, v23
	v_lshlrev_b32_e32 v58, 16, v24
	v_and_b32_e32 v59, 0xffff0000, v24
	v_lshlrev_b32_e32 v60, 16, v25
	v_and_b32_e32 v61, 0xffff0000, v25
	v_lshlrev_b32_e32 v24, 16, v18
	v_and_b32_e32 v25, 0xffff0000, v18
	v_lshlrev_b32_e32 v22, 16, v19
	v_and_b32_e32 v23, 0xffff0000, v19
	v_and_b32_e32 v63, 0xffff0000, v20
	v_lshlrev_b32_e32 v18, 16, v21
	v_and_b32_e32 v19, 0xffff0000, v21
	v_lshlrev_b32_e32 v64, 16, v38
	v_and_b32_e32 v65, 0xffff0000, v38
	v_lshlrev_b32_e32 v38, 16, v39
	v_and_b32_e32 v39, 0xffff0000, v39
	v_lshlrev_b32_e32 v66, 16, v40
	v_and_b32_e32 v67, 0xffff0000, v40
	v_lshlrev_b32_e32 v40, 16, v41
	v_and_b32_e32 v41, 0xffff0000, v41
	v_lshlrev_b32_e32 v68, 16, v46
	v_and_b32_e32 v69, 0xffff0000, v46
	v_lshlrev_b32_e32 v46, 16, v47
	v_and_b32_e32 v47, 0xffff0000, v47
	v_lshlrev_b32_e32 v20, 16, v48
	v_and_b32_e32 v21, 0xffff0000, v48
	v_lshlrev_b32_e32 v48, 16, v49
	v_and_b32_e32 v49, 0xffff0000, v49
	v_lshlrev_b32_e32 v84, 16, v34
	v_and_b32_e32 v85, 0xffff0000, v34
	v_lshlrev_b32_e32 v86, 16, v35
	v_and_b32_e32 v87, 0xffff0000, v35
	v_lshlrev_b32_e32 v88, 16, v36
	v_and_b32_e32 v89, 0xffff0000, v36
	v_lshlrev_b32_e32 v90, 16, v37
	v_and_b32_e32 v91, 0xffff0000, v37
	v_pk_add_f32 v[18:19], v[48:49], v[18:19]
	v_pk_add_f32 v[20:21], v[20:21], v[62:63]
	v_pk_add_f32 v[22:23], v[46:47], v[22:23]
	v_pk_add_f32 v[24:25], v[68:69], v[24:25]
	v_pk_add_f32 v[34:35], v[40:41], v[60:61]
	v_pk_add_f32 v[36:37], v[66:67], v[58:59]
	v_pk_add_f32 v[38:39], v[38:39], v[56:57]
	v_pk_add_f32 v[40:41], v[64:65], v[54:55]
	v_lshlrev_b32_e32 v80, 16, v52
	v_and_b32_e32 v81, 0xffff0000, v52
	v_lshlrev_b32_e32 v82, 16, v53
	v_and_b32_e32 v83, 0xffff0000, v53
	v_mov_b32_e32 v48, v21
	v_mov_b32_e32 v49, v19
	v_mul_f32_e32 v62, 0xbfb8aa3b, v88
	v_mul_f32_e32 v63, 0xbfb8aa3b, v89
	v_mov_b32_e32 v52, v25
	v_mov_b32_e32 v53, v23
	v_mov_b32_e32 v56, v37
	v_mov_b32_e32 v57, v35
	v_pk_mul_f32 v[58:59], v[38:39], v[38:39]
	v_pk_mul_f32 v[60:61], v[40:41], v[40:41]
	v_lshlrev_b32_e32 v76, 16, v50
	v_and_b32_e32 v77, 0xffff0000, v50
	v_lshlrev_b32_e32 v78, 16, v51
	v_and_b32_e32 v79, 0xffff0000, v51
	v_mov_b32_e32 v46, v20
	v_mov_b32_e32 v47, v18
	v_mov_b32_e32 v50, v24
	v_mov_b32_e32 v51, v22
	v_mul_f32_e32 v66, 0xbfb8aa3b, v84
	v_mul_f32_e32 v67, 0xbfb8aa3b, v85
	v_mov_b32_e32 v54, v36
	v_mov_b32_e32 v55, v34
	v_pk_mul_f32 v[48:49], v[48:49], v[48:49]
	v_exp_f32_e32 v62, v62
	v_exp_f32_e32 v63, v63
	v_pk_mul_f32 v[52:53], v[52:53], v[52:53]
	v_pk_mul_f32 v[56:57], v[56:57], v[56:57]
	v_add_f32_e32 v94, v58, v59
	v_add_f32_e32 v60, v60, v61
	v_mul_f32_e32 v92, 0xbfb8aa3b, v90
	v_mul_f32_e32 v93, 0xbfb8aa3b, v91
	v_exp_f32_e32 v66, v66
	v_exp_f32_e32 v67, v67
	v_pk_fma_f32 v[46:47], v[46:47], v[46:47], v[48:49]
	v_pk_fma_f32 v[48:49], v[50:51], v[50:51], v[52:53]
	v_pk_fma_f32 v[50:51], v[54:55], v[54:55], v[56:57]
	v_add_f32_e32 v52, v60, v94
	v_mul_f32_e32 v64, 0xbfb8aa3b, v86
	v_mul_f32_e32 v65, 0xbfb8aa3b, v87
	v_mul_f32_e32 v68, 0xbfb8aa3b, v82
	v_mul_f32_e32 v69, 0xbfb8aa3b, v83
	v_exp_f32_e32 v58, v92
	v_exp_f32_e32 v59, v93
	v_add_f32_e32 v50, v52, v50
	v_mul_f32_e32 v70, 0xbfb8aa3b, v80
	v_mul_f32_e32 v71, 0xbfb8aa3b, v81
	v_exp_f32_e32 v64, v64
	v_exp_f32_e32 v65, v65
	v_exp_f32_e32 v68, v68
	v_exp_f32_e32 v69, v69
	v_add_f32_e32 v92, v50, v51
	v_mul_f32_e32 v72, 0xbfb8aa3b, v78
	v_mul_f32_e32 v73, 0xbfb8aa3b, v79
	v_exp_f32_e32 v70, v70
	v_exp_f32_e32 v71, v71
	v_pk_add_f32 v[50:51], v[62:63], 1.0 op_sel_hi:[1,0]
	v_add_f32_e32 v48, v92, v48
	v_mul_f32_e32 v74, 0xbfb8aa3b, v76
	v_mul_f32_e32 v75, 0xbfb8aa3b, v77
	v_exp_f32_e32 v72, v72
	v_exp_f32_e32 v73, v73
	v_pk_add_f32 v[54:55], v[66:67], 1.0 op_sel_hi:[1,0]
	v_div_scale_f32 v66, s[4:5], v51, v51, v89
	v_add_f32_e32 v48, v48, v49
	v_exp_f32_e32 v74, v74
	v_exp_f32_e32 v75, v75
	v_pk_add_f32 v[58:59], v[58:59], 1.0 op_sel_hi:[1,0]
	v_rcp_f32_e32 v113, v66
	v_add_f32_e32 v46, v48, v46
	v_pk_add_f32 v[52:53], v[64:65], 1.0 op_sel_hi:[1,0]
	v_pk_add_f32 v[56:57], v[68:69], 1.0 op_sel_hi:[1,0]
	v_div_scale_f32 v68, s[4:5], v50, v50, v88
	v_div_scale_f32 v49, s[4:5], v59, v59, v91
	v_add_f32_e32 v46, v46, v47
	v_pk_add_f32 v[60:61], v[70:71], 1.0 op_sel_hi:[1,0]
	v_div_scale_f32 v70, s[4:5], v53, v53, v87
	v_rcp_f32_e32 v114, v68
	v_rcp_f32_e32 v127, v49
	ds_bpermute_b32 v47, v42, v46
	v_pk_add_f32 v[62:63], v[72:73], 1.0 op_sel_hi:[1,0]
	v_div_scale_f32 v72, s[4:5], v52, v52, v86
	v_div_scale_f32 v111, s[4:5], v58, v58, v90
	v_rcp_f32_e32 v115, v70
	v_pk_add_f32 v[64:65], v[74:75], 1.0 op_sel_hi:[1,0]
	v_div_scale_f32 v74, s[4:5], v55, v55, v85
	v_div_scale_f32 v94, s[4:5], v57, v57, v83
	v_rcp_f32_e32 v116, v72
	v_rcp_f32_e32 v128, v111
	v_fma_f32 v48, -v66, v113, 1.0
	v_div_scale_f32 v67, vcc, v89, v51, v89
	v_div_scale_f32 v92, s[4:5], v54, v54, v84
	v_rcp_f32_e32 v117, v74
	v_rcp_f32_e32 v119, v94
	v_fmac_f32_e32 v113, v48, v113
	v_rcp_f32_e32 v118, v92
	v_fma_f32 v129, -v68, v114, 1.0
	v_fma_f32 v144, -v49, v127, 1.0
	v_mul_f32_e32 v48, v67, v113
	v_div_scale_f32 v69, s[34:35], v88, v50, v88
	v_div_scale_f32 v96, s[4:5], v56, v56, v82
	v_div_scale_f32 v110, s[8:9], v91, v59, v91
	v_fma_f32 v132, -v70, v115, 1.0
	v_fmac_f32_e32 v114, v129, v114
	v_fmac_f32_e32 v127, v144, v127
	v_fma_f32 v146, -v66, v48, v67
	s_waitcnt lgkmcnt(0)
	v_add_f32_e32 v160, v46, v47
	v_div_scale_f32 v71, s[30:31], v87, v53, v87
	v_div_scale_f32 v98, s[4:5], v61, v61, v81
	v_div_scale_f32 v100, s[4:5], v60, v60, v80
	v_div_scale_f32 v102, s[4:5], v63, v63, v79
	v_div_scale_f32 v104, s[4:5], v62, v62, v78
	v_div_scale_f32 v106, s[4:5], v65, v65, v77
	v_div_scale_f32 v108, s[4:5], v64, v64, v76
	v_rcp_f32_e32 v120, v96
	v_fma_f32 v133, -v72, v116, 1.0
	v_fma_f32 v145, -v111, v128, 1.0
	v_fmac_f32_e32 v115, v132, v115
	v_mul_f32_e32 v129, v69, v114
	v_mul_f32_e32 v144, v110, v127
	v_fmac_f32_e32 v48, v146, v113
	ds_bpermute_b32 v146, v43, v160
	v_div_scale_f32 v73, s[28:29], v86, v52, v86
	v_div_scale_f32 v112, s[4:5], v90, v58, v90
	v_rcp_f32_e32 v121, v98
	v_fma_f32 v134, -v74, v117, 1.0
	v_fma_f32 v136, -v94, v119, 1.0
	v_fmac_f32_e32 v116, v133, v116
	v_fmac_f32_e32 v128, v145, v128
	v_mul_f32_e32 v132, v71, v115
	v_fma_f32 v147, -v68, v129, v69
	v_fma_f32 v46, -v49, v144, v110
	v_div_scale_f32 v75, s[26:27], v85, v55, v85
	v_div_scale_f32 v95, s[22:23], v83, v57, v83
	v_rcp_f32_e32 v122, v100
	v_fma_f32 v135, -v92, v118, 1.0
	v_fmac_f32_e32 v117, v134, v117
	v_fmac_f32_e32 v119, v136, v119
	v_mul_f32_e32 v133, v73, v116
	v_mul_f32_e32 v145, v112, v128
	v_fma_f32 v148, -v70, v132, v71
	v_fmac_f32_e32 v129, v147, v114
	v_fmac_f32_e32 v144, v46, v127
	v_fma_f32 v46, -v66, v48, v67
	v_div_scale_f32 v93, s[24:25], v84, v54, v84
	v_rcp_f32_e32 v123, v102
	v_fmac_f32_e32 v118, v135, v118
	v_mul_f32_e32 v134, v75, v117
	v_mul_f32_e32 v136, v95, v119
	v_fma_f32 v149, -v72, v133, v73
	v_fma_f32 v47, -v111, v145, v112
	v_fmac_f32_e32 v132, v148, v115
	v_fma_f32 v66, -v68, v129, v69
	v_div_fmas_f32 v46, v46, v113, v48
	s_mov_b64 vcc, s[34:35]
	v_rcp_f32_e32 v124, v104
	v_fma_f32 v137, -v96, v120, 1.0
	v_mul_f32_e32 v135, v93, v118
	v_fma_f32 v150, -v74, v134, v75
	v_fma_f32 v152, -v94, v136, v95
	v_fmac_f32_e32 v133, v149, v116
	v_fmac_f32_e32 v145, v47, v128
	v_fma_f32 v67, -v70, v132, v71
	v_div_fixup_f32 v47, v46, v51, v89
	v_div_fmas_f32 v46, v66, v114, v129
	s_mov_b64 vcc, s[30:31]
	v_div_scale_f32 v97, s[20:21], v82, v56, v82
	v_rcp_f32_e32 v125, v106
	v_fma_f32 v138, -v98, v121, 1.0
	v_fmac_f32_e32 v120, v137, v120
	v_fma_f32 v151, -v92, v135, v93
	v_fmac_f32_e32 v134, v150, v117
	v_fmac_f32_e32 v136, v152, v119
	v_fma_f32 v68, -v72, v133, v73
	v_div_fmas_f32 v48, v67, v115, v132
	s_mov_b64 vcc, s[28:29]
	s_waitcnt lgkmcnt(0)
	v_add_f32_e32 v66, v160, v146
	v_div_scale_f32 v99, s[18:19], v81, v61, v81
	v_rcp_f32_e32 v126, v108
	v_fma_f32 v139, -v100, v122, 1.0
	v_fmac_f32_e32 v121, v138, v121
	v_mul_f32_e32 v137, v97, v120
	v_fmac_f32_e32 v135, v151, v118
	v_fma_f32 v69, -v74, v134, v75
	v_fma_f32 v71, -v94, v136, v95
	v_fma_f32 v95, -v49, v144, v110
	v_div_fixup_f32 v49, v48, v53, v87
	v_div_fmas_f32 v48, v68, v116, v133
	s_mov_b64 vcc, s[26:27]
	ds_bpermute_b32 v67, v44, v66
	v_div_scale_f32 v101, s[16:17], v80, v60, v80
	v_fma_f32 v140, -v102, v123, 1.0
	v_fmac_f32_e32 v122, v139, v122
	v_mul_f32_e32 v138, v99, v121
	v_fma_f32 v153, -v96, v137, v97
	v_fma_f32 v70, -v92, v135, v93
	v_div_fixup_f32 v46, v46, v50, v88
	v_div_fmas_f32 v50, v69, v117, v134
	s_mov_b64 vcc, s[24:25]
	v_div_scale_f32 v103, s[14:15], v79, v63, v79
	v_fma_f32 v141, -v104, v124, 1.0
	v_fmac_f32_e32 v123, v140, v123
	v_mul_f32_e32 v139, v101, v122
	v_fma_f32 v154, -v98, v138, v99
	v_fmac_f32_e32 v137, v153, v120
	v_div_fixup_f32 v51, v50, v55, v85
	v_div_fmas_f32 v50, v70, v118, v135
	s_mov_b64 vcc, s[22:23]
	v_div_scale_f32 v105, s[12:13], v78, v62, v78
	v_fma_f32 v142, -v106, v125, 1.0
	v_fmac_f32_e32 v124, v141, v124
	v_mul_f32_e32 v140, v103, v123
	v_fma_f32 v155, -v100, v139, v101
	v_fmac_f32_e32 v138, v154, v121
	v_fma_f32 v72, -v96, v137, v97
	v_div_fixup_f32 v48, v48, v52, v86
	v_div_fmas_f32 v52, v71, v119, v136
	s_mov_b64 vcc, s[20:21]
	v_div_scale_f32 v107, s[10:11], v77, v65, v77
	v_fma_f32 v143, -v108, v126, 1.0
	v_fmac_f32_e32 v125, v142, v125
	v_mul_f32_e32 v141, v105, v124
	v_fma_f32 v156, -v102, v140, v103
	v_fmac_f32_e32 v139, v155, v122
	v_fma_f32 v73, -v98, v138, v99
	v_div_fixup_f32 v53, v52, v57, v83
	v_div_fmas_f32 v52, v72, v120, v137
	s_mov_b64 vcc, s[18:19]
	v_div_scale_f32 v109, s[6:7], v76, v64, v76
	v_fmac_f32_e32 v126, v143, v126
	v_mul_f32_e32 v142, v107, v125
	v_fma_f32 v157, -v104, v141, v105
	v_fmac_f32_e32 v140, v156, v123
	v_fma_f32 v74, -v100, v139, v101
	v_div_fixup_f32 v50, v50, v54, v84
	v_div_fmas_f32 v54, v73, v121, v138
	s_mov_b64 vcc, s[16:17]
	s_waitcnt lgkmcnt(0)
	v_add_f32_e32 v66, v66, v67
	v_mul_f32_e32 v143, v109, v126
	v_fma_f32 v158, -v106, v142, v107
	v_fmac_f32_e32 v141, v157, v124
	v_fma_f32 v75, -v102, v140, v103
	v_div_fixup_f32 v55, v54, v61, v81
	v_div_fmas_f32 v54, v74, v122, v139
	s_mov_b64 vcc, s[14:15]
	ds_bpermute_b32 v67, v45, v66
	v_fma_f32 v159, -v108, v143, v109
	v_fmac_f32_e32 v142, v158, v125
	v_fma_f32 v92, -v104, v141, v105
	v_div_fixup_f32 v52, v52, v56, v82
	v_div_fmas_f32 v56, v75, v123, v140
	s_mov_b64 vcc, s[12:13]
	v_fmac_f32_e32 v143, v159, v126
	v_fma_f32 v93, -v106, v142, v107
	v_div_fixup_f32 v57, v56, v63, v79
	v_div_fmas_f32 v56, v92, v124, v141
	s_mov_b64 vcc, s[10:11]
	v_fma_f32 v94, -v108, v143, v109
	v_div_fixup_f32 v54, v54, v60, v80
	v_div_fmas_f32 v60, v93, v125, v142
	s_mov_b64 vcc, s[6:7]
	v_div_fixup_f32 v61, v60, v65, v77
	v_div_fmas_f32 v60, v94, v126, v143
	s_mov_b64 vcc, s[8:9]
	v_fma_f32 v96, -v111, v145, v112
	v_div_fixup_f32 v56, v56, v62, v78
	v_div_fmas_f32 v62, v95, v127, v144
	s_waitcnt lgkmcnt(0)
	v_add_f32_e32 v63, v66, v67
	s_mov_b64 vcc, s[4:5]
	v_div_fixup_f32 v59, v62, v59, v91
	v_div_fmas_f32 v62, v96, v128, v145
	v_fmamk_f32 v63, v63, 0x3b800000, v27
	v_div_fixup_f32 v58, v62, v58, v90
	v_mul_f32_e32 v62, 0x4b800000, v63
	v_cmp_gt_f32_e32 vcc, s58, v63
	v_div_fixup_f32 v60, v60, v64, v76
	s_nop 0
	v_cndmask_b32_e32 v62, v63, v62, vcc
	v_rsq_f32_e32 v62, v62
	s_nop 0
	v_mul_f32_e32 v63, 0x45800000, v62
	v_cndmask_b32_e32 v62, v62, v63, vcc
	v_pk_mul_f32 v[40:41], v[40:41], v[62:63] op_sel_hi:[1,0]
	v_pk_mul_f32 v[38:39], v[38:39], v[62:63] op_sel_hi:[1,0]
	v_pk_mul_f32 v[36:37], v[36:37], v[62:63] op_sel_hi:[1,0]
	v_pk_mul_f32 v[34:35], v[34:35], v[62:63] op_sel_hi:[1,0]
	v_pk_mul_f32 v[24:25], v[24:25], v[62:63] op_sel_hi:[1,0]
	v_pk_mul_f32 v[22:23], v[22:23], v[62:63] op_sel_hi:[1,0]
	v_pk_mul_f32 v[20:21], v[20:21], v[62:63] op_sel_hi:[1,0]
	v_pk_mul_f32 v[18:19], v[18:19], v[62:63] op_sel_hi:[1,0]
	v_pk_mul_f32 v[14:15], v[14:15], v[40:41]
	v_pk_mul_f32 v[16:17], v[16:17], v[38:39]
	v_pk_mul_f32 v[10:11], v[10:11], v[36:37]
	v_pk_mul_f32 v[12:13], v[12:13], v[34:35]
	v_pk_mul_f32 v[6:7], v[6:7], v[24:25]
	v_pk_mul_f32 v[8:9], v[22:23], v[8:9]
	v_pk_mul_f32 v[2:3], v[20:21], v[2:3]
	v_pk_mul_f32 v[4:5], v[18:19], v[4:5]
	v_pk_mul_f32 v[14:15], v[60:61], v[14:15]
	v_pk_mul_f32 v[16:17], v[56:57], v[16:17]
	v_pk_mul_f32 v[10:11], v[54:55], v[10:11]
	v_pk_mul_f32 v[12:13], v[52:53], v[12:13]
	v_pk_mul_f32 v[6:7], v[50:51], v[6:7]
	v_pk_mul_f32 v[8:9], v[48:49], v[8:9]
	v_pk_mul_f32 v[18:19], v[46:47], v[2:3]
	v_pk_mul_f32 v[20:21], v[58:59], v[4:5]
	v_cvt_pk_bf16_f32 v2, v14, v15
	v_cvt_pk_bf16_f32 v3, v16, v17
	v_cvt_pk_bf16_f32 v4, v10, v11
	v_cvt_pk_bf16_f32 v5, v12, v13
	v_cvt_pk_bf16_f32 v6, v6, v7
	v_cvt_pk_bf16_f32 v7, v8, v9
	v_cvt_pk_bf16_f32 v8, v18, v19
	v_cvt_pk_bf16_f32 v9, v20, v21
	global_store_dwordx4 v[32:33], v[2:5], off offset:-28
	global_store_dwordx4 v[32:33], v[6:9], off offset:-12
	s_waitcnt vmcnt(2)
	s_andn2_b64 exec, exec, s[52:53]
	s_cbranch_execnz .LBB0_492
	s_waitcnt vmcnt(0)

.LBB0_1229:
	s_cmp_gt_i32 s44, 14
	s_cselect_b64 s[2:3], -1, 0
	s_cmp_lt_i32 s45, 15
	s_cselect_b64 s[4:5], -1, 0
	s_or_b64 s[2:3], s[2:3], s[4:5]
	s_and_b64 vcc, exec, s[2:3]
	s_cbranch_vccnz .LBB0_1287
	s_load_dword s33, s[0:1], 0xf0
	s_waitcnt vmcnt(1)
	v_lshl_or_b32 v26, s66, 2, v131
	s_add_u32 s2, s0, 0xf0
	s_movk_i32 s4, 0x3000
	v_and_b32_e32 v1, 0x3ff, v0
	s_addc_u32 s3, s1, 0
	v_cmp_gt_i32_e32 vcc, s4, v26
	s_and_saveexec_b64 s[36:37], vcc
	s_cbranch_execz .LBB0_1233
	v_mbcnt_lo_u32_b32 v2, -1, 0
	v_mbcnt_hi_u32_b32 v2, -1, v2
	v_and_b32_e32 v4, 64, v2
	v_xor_b32_e32 v3, 1, v2
	v_add_u32_e32 v4, 64, v4
	v_cmp_lt_i32_e32 vcc, v3, v4
	v_ashrrev_i32_e32 v27, 31, v26
	s_waitcnt lgkmcnt(0)
	s_lshl_b32 s46, s33, 2
	v_cndmask_b32_e32 v3, v2, v3, vcc
	v_lshlrev_b32_e32 v42, 2, v3
	v_xor_b32_e32 v3, 2, v2
	v_cmp_lt_i32_e32 vcc, v3, v4
	s_mov_b64 s[4:5], 0x18d2401c
	s_ashr_i32 s47, s46, 31
	v_cndmask_b32_e32 v3, v2, v3, vcc
	v_lshlrev_b32_e32 v43, 2, v3
	v_xor_b32_e32 v3, 4, v2
	v_cmp_lt_i32_e32 vcc, v3, v4
	s_mov_b32 s52, 0xfe7fffe4
	s_mov_b32 s54, 0xf85fffe4
	v_cndmask_b32_e32 v3, v2, v3, vcc
	v_lshlrev_b32_e32 v44, 2, v3
	v_xor_b32_e32 v3, 8, v2
	v_cmp_lt_i32_e32 vcc, v3, v4
	v_and_b32_e32 v4, 63, v1
	s_lshl_b64 s[48:49], s[46:47], 11
	v_cndmask_b32_e32 v2, v2, v3, vcc
	v_lshlrev_b32_e32 v45, 2, v2
	v_lshlrev_b32_e32 v2, 6, v1
	v_and_b32_e32 v2, 0x3c0, v2
	v_mov_b32_e32 v3, 0
	v_lshl_add_u64 v[28:29], s[92:93], 0, v[2:3]
	v_lshlrev_b64 v[2:3], 11, v[26:27]
	v_lshl_or_b32 v2, v4, 5, v2
	v_lshl_add_u64 v[2:3], s[42:43], 0, v[2:3]
	s_waitcnt vmcnt(0)
	v_lshl_add_u64 v[30:31], v[2:3], 0, s[4:5]
	s_mov_b64 s[50:51], 0
	s_mov_b32 s53, -1
	s_mov_b32 s55, -1
	s_mov_b32 s47, 0xf8600000
	v_mov_b32_e32 v27, 0x358637bd
	s_mov_b32 s56, 0x800000
	s_movk_i32 s57, 0x2fff
	s_mov_b32 s98, 0xfe800000
	s_mov_b32 s99, -1
	s_mov_b32 s100, 0xf8600000
	s_mov_b32 s101, -1
	global_load_dwordx4 v[200:203], v[30:31], off offset:-12
	global_load_dwordx4 v[204:207], v[30:31], off offset:-28
	v_lshl_add_u64 v[208:209], v[30:31], 0, s[98:99]
	global_load_dwordx4 v[208:211], v[208:209], off offset:-28
	v_lshl_add_u64 v[212:213], v[30:31], 0, s[52:53]
	global_load_dwordx4 v[212:215], v[212:213], off offset:16
	v_lshl_add_u64 v[216:217], v[30:31], 0, s[100:101]
	global_load_dwordx4 v[216:219], v[216:217], off offset:-28
	v_lshl_add_u64 v[220:221], v[30:31], 0, s[54:55]
	global_load_dwordx4 v[220:223], v[220:221], off offset:16
	s_waitcnt vmcnt(0)
.LBB0_1232:
	v_lshl_add_u64 v[32:33], v[30:31], 0, s[98:99]
	v_mov_b32_e32 v18, v200
	v_mov_b32_e32 v19, v201
	v_mov_b32_e32 v20, v202
	v_mov_b32_e32 v21, v203
	v_mov_b32_e32 v22, v204
	v_mov_b32_e32 v23, v205
	v_mov_b32_e32 v24, v206
	v_mov_b32_e32 v25, v207
	v_mov_b32_e32 v38, v208
	v_mov_b32_e32 v39, v209
	v_mov_b32_e32 v40, v210
	v_mov_b32_e32 v41, v211
	v_mov_b32_e32 v46, v212
	v_mov_b32_e32 v47, v213
	v_mov_b32_e32 v48, v214
	v_mov_b32_e32 v49, v215
	v_mov_b32_e32 v50, v216
	v_mov_b32_e32 v51, v217
	v_mov_b32_e32 v52, v218
	v_mov_b32_e32 v53, v219
	v_mov_b32_e32 v54, v220
	v_mov_b32_e32 v55, v221
	v_mov_b32_e32 v56, v222
	v_mov_b32_e32 v57, v223
	global_load_dwordx4 v[2:5], v[28:29], off offset:1072
	global_load_dwordx4 v[6:9], v[28:29], off offset:1056
	global_load_dwordx4 v[10:13], v[28:29], off offset:1040
	global_load_dwordx4 v[14:17], v[28:29], off offset:1024
	v_add_u32_e32 v26, s46, v26
	v_cmp_lt_i32_e64 s[4:5], s57, v26
	s_or_b64 s[50:51], s[4:5], s[50:51]
	v_lshl_add_u64 v[30:31], v[30:31], 0, s[48:49]
	global_load_dwordx4 v[200:203], v[30:31], off offset:-12
	global_load_dwordx4 v[204:207], v[30:31], off offset:-28
	v_lshl_add_u64 v[208:209], v[30:31], 0, s[98:99]
	global_load_dwordx4 v[208:211], v[208:209], off offset:-28
	v_lshl_add_u64 v[212:213], v[30:31], 0, s[52:53]
	global_load_dwordx4 v[212:215], v[212:213], off offset:16
	v_lshl_add_u64 v[216:217], v[30:31], 0, s[100:101]
	global_load_dwordx4 v[216:219], v[216:217], off offset:-28
	v_lshl_add_u64 v[220:221], v[30:31], 0, s[54:55]
	global_load_dwordx4 v[220:223], v[220:221], off offset:16
	s_waitcnt vmcnt(6)
	v_lshlrev_b32_e32 v62, 16, v20
	v_lshlrev_b32_e32 v58, 16, v22
	v_and_b32_e32 v59, 0xffff0000, v22
	v_lshlrev_b32_e32 v60, 16, v23
	v_and_b32_e32 v61, 0xffff0000, v23
	v_lshlrev_b32_e32 v36, 16, v24
	v_and_b32_e32 v37, 0xffff0000, v24
	v_lshlrev_b32_e32 v34, 16, v25
	v_and_b32_e32 v35, 0xffff0000, v25
	v_lshlrev_b32_e32 v24, 16, v18
	v_and_b32_e32 v25, 0xffff0000, v18
	v_lshlrev_b32_e32 v22, 16, v19
	v_and_b32_e32 v23, 0xffff0000, v19
	v_and_b32_e32 v63, 0xffff0000, v20
	v_lshlrev_b32_e32 v18, 16, v21
	v_and_b32_e32 v19, 0xffff0000, v21
	v_lshlrev_b32_e32 v64, 16, v38
	v_and_b32_e32 v65, 0xffff0000, v38
	v_lshlrev_b32_e32 v38, 16, v39
	v_and_b32_e32 v39, 0xffff0000, v39
	v_lshlrev_b32_e32 v66, 16, v40
	v_and_b32_e32 v67, 0xffff0000, v40
	v_lshlrev_b32_e32 v40, 16, v41
	v_and_b32_e32 v41, 0xffff0000, v41
	v_lshlrev_b32_e32 v68, 16, v46
	v_and_b32_e32 v69, 0xffff0000, v46
	v_lshlrev_b32_e32 v46, 16, v47
	v_and_b32_e32 v47, 0xffff0000, v47
	v_lshlrev_b32_e32 v20, 16, v48
	v_and_b32_e32 v21, 0xffff0000, v48
	v_lshlrev_b32_e32 v48, 16, v49
	v_and_b32_e32 v49, 0xffff0000, v49
	v_lshlrev_b32_e32 v88, 16, v56
	v_and_b32_e32 v89, 0xffff0000, v56
	v_pk_add_f32 v[18:19], v[48:49], v[18:19]
	v_pk_add_f32 v[20:21], v[20:21], v[62:63]
	v_pk_add_f32 v[22:23], v[46:47], v[22:23]
	v_pk_add_f32 v[24:25], v[68:69], v[24:25]
	v_pk_add_f32 v[34:35], v[40:41], v[34:35]
	v_pk_add_f32 v[36:37], v[66:67], v[36:37]
	v_pk_add_f32 v[38:39], v[38:39], v[60:61]
	v_pk_add_f32 v[40:41], v[64:65], v[58:59]
	v_lshlrev_b32_e32 v80, 16, v52
	v_and_b32_e32 v81, 0xffff0000, v52
	v_lshlrev_b32_e32 v82, 16, v53
	v_and_b32_e32 v83, 0xffff0000, v53
	v_lshlrev_b32_e32 v84, 16, v54
	v_and_b32_e32 v85, 0xffff0000, v54
	v_lshlrev_b32_e32 v90, 16, v57
	v_and_b32_e32 v91, 0xffff0000, v57
	v_mov_b32_e32 v48, v21
	v_mov_b32_e32 v49, v19
	v_mul_f32_e32 v62, 0xbfb8aa3b, v88
	v_mul_f32_e32 v63, 0xbfb8aa3b, v89
	v_mov_b32_e32 v52, v25
	v_mov_b32_e32 v53, v23
	v_mov_b32_e32 v56, v37
	v_mov_b32_e32 v57, v35
	v_pk_mul_f32 v[58:59], v[38:39], v[38:39]
	v_pk_mul_f32 v[60:61], v[40:41], v[40:41]
	v_lshlrev_b32_e32 v76, 16, v50
	v_and_b32_e32 v77, 0xffff0000, v50
	v_lshlrev_b32_e32 v78, 16, v51
	v_and_b32_e32 v79, 0xffff0000, v51
	v_lshlrev_b32_e32 v86, 16, v55
	v_and_b32_e32 v87, 0xffff0000, v55
	v_mov_b32_e32 v46, v20
	v_mov_b32_e32 v47, v18
	v_mov_b32_e32 v50, v24
	v_mov_b32_e32 v51, v22
	v_mul_f32_e32 v66, 0xbfb8aa3b, v84
	v_mul_f32_e32 v67, 0xbfb8aa3b, v85
	v_mov_b32_e32 v54, v36
	v_mov_b32_e32 v55, v34
	v_pk_mul_f32 v[48:49], v[48:49], v[48:49]
	v_exp_f32_e32 v62, v62
	v_exp_f32_e32 v63, v63
	v_pk_mul_f32 v[52:53], v[52:53], v[52:53]
	v_pk_mul_f32 v[56:57], v[56:57], v[56:57]
	v_add_f32_e32 v94, v58, v59
	v_add_f32_e32 v60, v60, v61
	v_mul_f32_e32 v92, 0xbfb8aa3b, v90
	v_mul_f32_e32 v93, 0xbfb8aa3b, v91
	v_exp_f32_e32 v66, v66
	v_exp_f32_e32 v67, v67
	v_pk_fma_f32 v[46:47], v[46:47], v[46:47], v[48:49]
	v_pk_fma_f32 v[48:49], v[50:51], v[50:51], v[52:53]
	v_pk_fma_f32 v[50:51], v[54:55], v[54:55], v[56:57]
	v_add_f32_e32 v52, v60, v94
	v_mul_f32_e32 v64, 0xbfb8aa3b, v86
	v_mul_f32_e32 v65, 0xbfb8aa3b, v87
	v_mul_f32_e32 v68, 0xbfb8aa3b, v82
	v_mul_f32_e32 v69, 0xbfb8aa3b, v83
	v_exp_f32_e32 v58, v92
	v_exp_f32_e32 v59, v93
	v_add_f32_e32 v50, v52, v50
	v_mul_f32_e32 v70, 0xbfb8aa3b, v80
	v_mul_f32_e32 v71, 0xbfb8aa3b, v81
	v_exp_f32_e32 v64, v64
	v_exp_f32_e32 v65, v65
	v_exp_f32_e32 v68, v68
	v_exp_f32_e32 v69, v69
	v_add_f32_e32 v92, v50, v51
	v_mul_f32_e32 v72, 0xbfb8aa3b, v78
	v_mul_f32_e32 v73, 0xbfb8aa3b, v79
	v_exp_f32_e32 v70, v70
	v_exp_f32_e32 v71, v71
	v_pk_add_f32 v[50:51], v[62:63], 1.0 op_sel_hi:[1,0]
	v_add_f32_e32 v48, v92, v48
	v_mul_f32_e32 v74, 0xbfb8aa3b, v76
	v_mul_f32_e32 v75, 0xbfb8aa3b, v77
	v_exp_f32_e32 v72, v72
	v_exp_f32_e32 v73, v73
	v_pk_add_f32 v[54:55], v[66:67], 1.0 op_sel_hi:[1,0]
	v_div_scale_f32 v66, s[4:5], v51, v51, v89
	v_add_f32_e32 v48, v48, v49
	v_exp_f32_e32 v74, v74
	v_exp_f32_e32 v75, v75
	v_pk_add_f32 v[58:59], v[58:59], 1.0 op_sel_hi:[1,0]
	v_rcp_f32_e32 v113, v66
	v_add_f32_e32 v46, v48, v46
	v_pk_add_f32 v[52:53], v[64:65], 1.0 op_sel_hi:[1,0]
	v_pk_add_f32 v[56:57], v[68:69], 1.0 op_sel_hi:[1,0]
	v_div_scale_f32 v68, s[4:5], v50, v50, v88
	v_div_scale_f32 v49, s[4:5], v59, v59, v91
	v_add_f32_e32 v46, v46, v47
	v_pk_add_f32 v[60:61], v[70:71], 1.0 op_sel_hi:[1,0]
	v_div_scale_f32 v70, s[4:5], v53, v53, v87
	v_rcp_f32_e32 v114, v68
	v_rcp_f32_e32 v127, v49
	ds_bpermute_b32 v47, v42, v46
	v_pk_add_f32 v[62:63], v[72:73], 1.0 op_sel_hi:[1,0]
	v_div_scale_f32 v72, s[4:5], v52, v52, v86
	v_div_scale_f32 v111, s[4:5], v58, v58, v90
	v_rcp_f32_e32 v115, v70
	v_pk_add_f32 v[64:65], v[74:75], 1.0 op_sel_hi:[1,0]
	v_div_scale_f32 v74, s[4:5], v55, v55, v85
	v_div_scale_f32 v94, s[4:5], v57, v57, v83
	v_rcp_f32_e32 v116, v72
	v_rcp_f32_e32 v128, v111
	v_fma_f32 v48, -v66, v113, 1.0
	v_div_scale_f32 v67, vcc, v89, v51, v89
	v_div_scale_f32 v92, s[4:5], v54, v54, v84
	v_rcp_f32_e32 v117, v74
	v_rcp_f32_e32 v119, v94
	v_fmac_f32_e32 v113, v48, v113
	v_rcp_f32_e32 v118, v92
	v_fma_f32 v129, -v68, v114, 1.0
	v_fma_f32 v144, -v49, v127, 1.0
	v_mul_f32_e32 v48, v67, v113
	v_div_scale_f32 v69, s[34:35], v88, v50, v88
	v_div_scale_f32 v96, s[4:5], v56, v56, v82
	v_div_scale_f32 v110, s[8:9], v91, v59, v91
	v_fma_f32 v132, -v70, v115, 1.0
	v_fmac_f32_e32 v114, v129, v114
	v_fmac_f32_e32 v127, v144, v127
	v_fma_f32 v146, -v66, v48, v67
	s_waitcnt lgkmcnt(0)
	v_add_f32_e32 v160, v46, v47
	v_div_scale_f32 v71, s[30:31], v87, v53, v87
	v_div_scale_f32 v98, s[4:5], v61, v61, v81
	v_div_scale_f32 v100, s[4:5], v60, v60, v80
	v_div_scale_f32 v102, s[4:5], v63, v63, v79
	v_div_scale_f32 v104, s[4:5], v62, v62, v78
	v_div_scale_f32 v106, s[4:5], v65, v65, v77
	v_div_scale_f32 v108, s[4:5], v64, v64, v76
	v_rcp_f32_e32 v120, v96
	v_fma_f32 v133, -v72, v116, 1.0
	v_fma_f32 v145, -v111, v128, 1.0
	v_fmac_f32_e32 v115, v132, v115
	v_mul_f32_e32 v129, v69, v114
	v_mul_f32_e32 v144, v110, v127
	v_fmac_f32_e32 v48, v146, v113
	ds_bpermute_b32 v146, v43, v160
	v_div_scale_f32 v73, s[28:29], v86, v52, v86
	v_div_scale_f32 v112, s[4:5], v90, v58, v90
	v_rcp_f32_e32 v121, v98
	v_fma_f32 v134, -v74, v117, 1.0
	v_fma_f32 v136, -v94, v119, 1.0
	v_fmac_f32_e32 v116, v133, v116
	v_fmac_f32_e32 v128, v145, v128
	v_mul_f32_e32 v132, v71, v115
	v_fma_f32 v147, -v68, v129, v69
	v_fma_f32 v46, -v49, v144, v110
	v_div_scale_f32 v75, s[26:27], v85, v55, v85
	v_div_scale_f32 v95, s[22:23], v83, v57, v83
	v_rcp_f32_e32 v122, v100
	v_fma_f32 v135, -v92, v118, 1.0
	v_fmac_f32_e32 v117, v134, v117
	v_fmac_f32_e32 v119, v136, v119
	v_mul_f32_e32 v133, v73, v116
	v_mul_f32_e32 v145, v112, v128
	v_fma_f32 v148, -v70, v132, v71
	v_fmac_f32_e32 v129, v147, v114
	v_fmac_f32_e32 v144, v46, v127
	v_fma_f32 v46, -v66, v48, v67
	v_div_scale_f32 v93, s[24:25], v84, v54, v84
	v_rcp_f32_e32 v123, v102
	v_fmac_f32_e32 v118, v135, v118
	v_mul_f32_e32 v134, v75, v117
	v_mul_f32_e32 v136, v95, v119
	v_fma_f32 v149, -v72, v133, v73
	v_fma_f32 v47, -v111, v145, v112
	v_fmac_f32_e32 v132, v148, v115
	v_fma_f32 v66, -v68, v129, v69
	v_div_fmas_f32 v46, v46, v113, v48
	s_mov_b64 vcc, s[34:35]
	v_rcp_f32_e32 v124, v104
	v_fma_f32 v137, -v96, v120, 1.0
	v_mul_f32_e32 v135, v93, v118
	v_fma_f32 v150, -v74, v134, v75
	v_fma_f32 v152, -v94, v136, v95
	v_fmac_f32_e32 v133, v149, v116
	v_fmac_f32_e32 v145, v47, v128
	v_fma_f32 v67, -v70, v132, v71
	v_div_fixup_f32 v47, v46, v51, v89
	v_div_fmas_f32 v46, v66, v114, v129
	s_mov_b64 vcc, s[30:31]
	v_div_scale_f32 v97, s[20:21], v82, v56, v82
	v_rcp_f32_e32 v125, v106
	v_fma_f32 v138, -v98, v121, 1.0
	v_fmac_f32_e32 v120, v137, v120
	v_fma_f32 v151, -v92, v135, v93
	v_fmac_f32_e32 v134, v150, v117
	v_fmac_f32_e32 v136, v152, v119
	v_fma_f32 v68, -v72, v133, v73
	v_div_fmas_f32 v48, v67, v115, v132
	s_mov_b64 vcc, s[28:29]
	s_waitcnt lgkmcnt(0)
	v_add_f32_e32 v66, v160, v146
	v_div_scale_f32 v99, s[18:19], v81, v61, v81
	v_rcp_f32_e32 v126, v108
	v_fma_f32 v139, -v100, v122, 1.0
	v_fmac_f32_e32 v121, v138, v121
	v_mul_f32_e32 v137, v97, v120
	v_fmac_f32_e32 v135, v151, v118
	v_fma_f32 v69, -v74, v134, v75
	v_fma_f32 v71, -v94, v136, v95
	v_fma_f32 v95, -v49, v144, v110
	v_div_fixup_f32 v49, v48, v53, v87
	v_div_fmas_f32 v48, v68, v116, v133
	s_mov_b64 vcc, s[26:27]
	ds_bpermute_b32 v67, v44, v66
	v_div_scale_f32 v101, s[16:17], v80, v60, v80
	v_fma_f32 v140, -v102, v123, 1.0
	v_fmac_f32_e32 v122, v139, v122
	v_mul_f32_e32 v138, v99, v121
	v_fma_f32 v153, -v96, v137, v97
	v_fma_f32 v70, -v92, v135, v93
	v_div_fixup_f32 v46, v46, v50, v88
	v_div_fmas_f32 v50, v69, v117, v134
	s_mov_b64 vcc, s[24:25]
	v_div_scale_f32 v103, s[14:15], v79, v63, v79
	v_fma_f32 v141, -v104, v124, 1.0
	v_fmac_f32_e32 v123, v140, v123
	v_mul_f32_e32 v139, v101, v122
	v_fma_f32 v154, -v98, v138, v99
	v_fmac_f32_e32 v137, v153, v120
	v_div_fixup_f32 v51, v50, v55, v85
	v_div_fmas_f32 v50, v70, v118, v135
	s_mov_b64 vcc, s[22:23]
	v_div_scale_f32 v105, s[12:13], v78, v62, v78
	v_fma_f32 v142, -v106, v125, 1.0
	v_fmac_f32_e32 v124, v141, v124
	v_mul_f32_e32 v140, v103, v123
	v_fma_f32 v155, -v100, v139, v101
	v_fmac_f32_e32 v138, v154, v121
	v_fma_f32 v72, -v96, v137, v97
	v_div_fixup_f32 v48, v48, v52, v86
	v_div_fmas_f32 v52, v71, v119, v136
	s_mov_b64 vcc, s[20:21]
	v_div_scale_f32 v107, s[10:11], v77, v65, v77
	v_fma_f32 v143, -v108, v126, 1.0
	v_fmac_f32_e32 v125, v142, v125
	v_mul_f32_e32 v141, v105, v124
	v_fma_f32 v156, -v102, v140, v103
	v_fmac_f32_e32 v139, v155, v122
	v_fma_f32 v73, -v98, v138, v99
	v_div_fixup_f32 v53, v52, v57, v83
	v_div_fmas_f32 v52, v72, v120, v137
	s_mov_b64 vcc, s[18:19]
	v_div_scale_f32 v109, s[6:7], v76, v64, v76
	v_fmac_f32_e32 v126, v143, v126
	v_mul_f32_e32 v142, v107, v125
	v_fma_f32 v157, -v104, v141, v105
	v_fmac_f32_e32 v140, v156, v123
	v_fma_f32 v74, -v100, v139, v101
	v_div_fixup_f32 v50, v50, v54, v84
	v_div_fmas_f32 v54, v73, v121, v138
	s_mov_b64 vcc, s[16:17]
	s_waitcnt lgkmcnt(0)
	v_add_f32_e32 v66, v66, v67
	v_mul_f32_e32 v143, v109, v126
	v_fma_f32 v158, -v106, v142, v107
	v_fmac_f32_e32 v141, v157, v124
	v_fma_f32 v75, -v102, v140, v103
	v_div_fixup_f32 v55, v54, v61, v81
	v_div_fmas_f32 v54, v74, v122, v139
	s_mov_b64 vcc, s[14:15]
	ds_bpermute_b32 v67, v45, v66
	v_fma_f32 v159, -v108, v143, v109
	v_fmac_f32_e32 v142, v158, v125
	v_fma_f32 v92, -v104, v141, v105
	v_div_fixup_f32 v52, v52, v56, v82
	v_div_fmas_f32 v56, v75, v123, v140
	s_mov_b64 vcc, s[12:13]
	v_fmac_f32_e32 v143, v159, v126
	v_fma_f32 v93, -v106, v142, v107
	v_div_fixup_f32 v57, v56, v63, v79
	v_div_fmas_f32 v56, v92, v124, v141
	s_mov_b64 vcc, s[10:11]
	v_fma_f32 v94, -v108, v143, v109
	v_div_fixup_f32 v54, v54, v60, v80
	v_div_fmas_f32 v60, v93, v125, v142
	s_mov_b64 vcc, s[6:7]
	v_div_fixup_f32 v61, v60, v65, v77
	v_div_fmas_f32 v60, v94, v126, v143
	s_mov_b64 vcc, s[8:9]
	v_fma_f32 v96, -v111, v145, v112
	v_div_fixup_f32 v56, v56, v62, v78
	v_div_fmas_f32 v62, v95, v127, v144
	s_waitcnt lgkmcnt(0)
	v_add_f32_e32 v63, v66, v67
	s_mov_b64 vcc, s[4:5]
	v_div_fixup_f32 v59, v62, v59, v91
	v_div_fmas_f32 v62, v96, v128, v145
	v_fmamk_f32 v63, v63, 0x3b800000, v27
	v_div_fixup_f32 v58, v62, v58, v90
	v_mul_f32_e32 v62, 0x4b800000, v63
	v_cmp_gt_f32_e32 vcc, s56, v63
	v_div_fixup_f32 v60, v60, v64, v76
	s_nop 0
	v_cndmask_b32_e32 v62, v63, v62, vcc
	v_rsq_f32_e32 v62, v62
	s_nop 0
	v_mul_f32_e32 v63, 0x45800000, v62
	v_cndmask_b32_e32 v62, v62, v63, vcc
	v_pk_mul_f32 v[40:41], v[40:41], v[62:63] op_sel_hi:[1,0]
	v_pk_mul_f32 v[38:39], v[38:39], v[62:63] op_sel_hi:[1,0]
	v_pk_mul_f32 v[36:37], v[36:37], v[62:63] op_sel_hi:[1,0]
	v_pk_mul_f32 v[34:35], v[34:35], v[62:63] op_sel_hi:[1,0]
	v_pk_mul_f32 v[24:25], v[24:25], v[62:63] op_sel_hi:[1,0]
	v_pk_mul_f32 v[22:23], v[22:23], v[62:63] op_sel_hi:[1,0]
	v_pk_mul_f32 v[20:21], v[20:21], v[62:63] op_sel_hi:[1,0]
	v_pk_mul_f32 v[18:19], v[18:19], v[62:63] op_sel_hi:[1,0]
	v_pk_mul_f32 v[14:15], v[14:15], v[40:41]
	v_pk_mul_f32 v[16:17], v[16:17], v[38:39]
	v_pk_mul_f32 v[10:11], v[10:11], v[36:37]
	v_pk_mul_f32 v[12:13], v[12:13], v[34:35]
	v_pk_mul_f32 v[6:7], v[6:7], v[24:25]
	v_pk_mul_f32 v[8:9], v[22:23], v[8:9]
	v_pk_mul_f32 v[2:3], v[20:21], v[2:3]
	v_pk_mul_f32 v[4:5], v[18:19], v[4:5]
	v_pk_mul_f32 v[14:15], v[60:61], v[14:15]
	v_pk_mul_f32 v[16:17], v[56:57], v[16:17]
	v_pk_mul_f32 v[10:11], v[54:55], v[10:11]
	v_pk_mul_f32 v[12:13], v[52:53], v[12:13]
	v_pk_mul_f32 v[6:7], v[50:51], v[6:7]
	v_pk_mul_f32 v[8:9], v[48:49], v[8:9]
	v_pk_mul_f32 v[18:19], v[46:47], v[2:3]
	v_pk_mul_f32 v[20:21], v[58:59], v[4:5]
	v_cvt_pk_bf16_f32 v2, v14, v15
	v_cvt_pk_bf16_f32 v3, v16, v17
	v_cvt_pk_bf16_f32 v4, v10, v11
	v_cvt_pk_bf16_f32 v5, v12, v13
	v_cvt_pk_bf16_f32 v6, v6, v7
	v_cvt_pk_bf16_f32 v7, v8, v9
	v_cvt_pk_bf16_f32 v8, v18, v19
	v_cvt_pk_bf16_f32 v9, v20, v21
	global_store_dwordx4 v[32:33], v[2:5], off offset:-28
	global_store_dwordx4 v[32:33], v[6:9], off offset:-12
	s_waitcnt vmcnt(2)
	s_andn2_b64 exec, exec, s[50:51]
	s_cbranch_execnz .LBB0_1232
	s_waitcnt vmcnt(0)
